# score-bound reference restricted to the grouped-query units (context units of the neighbourhood heads keep the running-max reference)
# baseline (speedup 1.0000x reference)
; #define L0_UNIT_G(i_, g_, ok_) do { ok_ = true; if ((i_) < 4) g_ = vcu * 4 + (i_); else { g_ = 1024 + vcu; if (vcu >= 64) ok_ = false; } if (G != 256) { g_ = (i_) * G + vcu; ok_ = g_ < nun; } if ((i_) >= per) ok_ = false; } while (0)
; template <int l> __device__ __forceinline__ void layer_body(const Args& a, unsigned char* lds, const XcdBarrier& bar, int G, int bx, int vcu, int gw, int NGW, int lane_, int tid_k, int wave) {
;     ...
;                 for (int i = 0; i < per; ++i) {
;                     AttnDesc d, d2; bool ok, ok2; int g, g2;
;                     L0_UNIT_G(i, g, ok); L0_UNIT_G(i + 1, g2, ok2);
;                     if (!ok) { pre = false; continue; }
;                     L0_UNIT_DESC(d, g); d2 = d; if (ok2) L0_UNIT_DESC(d2, g2);
.LBB0_458:
	s_cmp_lt_u32 s3, 4
	s_cselect_b64 s[6:7], -1, 0
	s_mul_i32 s15, s3, s34
	v_readlane_b32 s14, v254, 0
	s_or_b64 s[8:9], s[48:49], s[6:7]
	s_add_i32 s15, s15, s14
	s_cmpk_lt_i32 s15, 0x440
	v_cndmask_b32_e64 v0, 0, 1, s[8:9]
	s_cselect_b64 s[8:9], -1, 0
	v_cndmask_b32_e64 v2, 0, 1, s[8:9]
	v_cndmask_b32_e64 v0, v2, v0, s[4:5]
	v_and_b32_e32 v0, 1, v0
	v_cmp_eq_u32_e32 vcc, 0, v0
	s_add_i32 s14, s3, 1
	s_cbranch_vccnz .LBB0_476
	s_add_i32 s8, s3, s1
	s_and_b64 s[6:7], s[6:7], exec
	s_cselect_b32 s8, s8, s12
	s_and_b64 s[6:7], s[4:5], exec
	s_cselect_b32 s33, s8, s15
	s_mov_b32 s100, s99
	s_cmpk_lt_i32 s33, 0x400
	s_cselect_b64 s[8:9], -1, 0
	s_cmpk_gt_i32 s33, 0x3ff
	s_mov_b64 s[6:7], -1
	s_cbranch_scc0 .LBB0_465
	s_add_i32 s6, s33, 0xfffffc00
	s_lshr_b32 s39, s6, 4
	s_and_b32 s43, s33, 15
	s_mov_b64 s[6:7], -1
	s_cmp_gt_u32 s43, 7
	s_mul_hi_u32 s62, s39, 0x2520000
	s_mul_i32 s63, s39, 0x2520000
	s_cbranch_scc0 .LBB0_462
	s_add_i32 s6, s43, -8
	s_add_u32 s7, s44, s63
	s_addc_u32 s52, s45, s62
	s_lshl_b32 s64, s6, 7
	s_add_u32 s64, s7, s64
	s_addc_u32 s65, s52, 0
	s_add_u32 s78, s64, 0xc00
	s_addc_u32 s79, s65, 0
	s_lshl_b32 s6, s6, 5
	s_and_b32 s6, s6, 0xffffff80
	s_add_u32 s6, s7, s6
	s_addc_u32 s7, s52, 0
	s_add_u32 s70, s6, 0x1000
	s_addc_u32 s71, s7, 0
	s_add_u32 s72, s6, 0x1100
	s_addc_u32 s73, s7, 0
	s_lshl_b32 s52, s43, 6
	s_mov_b64 s[6:7], 0
.LBB0_462:
	s_andn2_b64 vcc, exec, s[6:7]
	s_cbranch_vccnz .LBB0_464
	s_mov_b32 s100, 0xff800000
	s_add_u32 s6, s44, s63
	s_addc_u32 s7, s45, s62
	s_lshl_b32 s52, s43, 6
	s_lshl_b32 s43, s43, 7
	s_add_u32 s78, s6, s43
	s_addc_u32 s79, s7, 0
	s_add_u32 s70, s78, 0x400
	s_addc_u32 s71, s79, 0
	s_add_u32 s72, s78, 0x800
	s_addc_u32 s73, s79, 0

; #define WAIT_BAR(N) asm volatile("s_waitcnt vmcnt(" #N ") lgkmcnt(0)\n\ts_barrier":::"memory")
;   #define DMA_K(t,slot) glds16(ksrc+(long)KROW(t)*PK,(unsigned)__builtin_amdgcn_readfirstlane(kdst+(slot)))
;   #define DMA_V(t,slot) do{ glds16(vsrc+(long)KROW(t)*PV,(unsigned)__builtin_amdgcn_readfirstlane(vdst+2*(slot))); if(MODE==2)glds16(vsrc+(long)KROW(t)*PV+64,(unsigned)__builtin_amdgcn_readfirstlane(vdst+2*(slot)+SLOTB)); }while(0)
;   #define CMASK(P0,P1,t) do{ if(MODE==1&&(t)>=4)na_apply(P0,P1,mf,na_rowok((t),nabase,nar)); }while(0)
;   #define START(P0,P1) do{ const float rm=rowmax(P0,P1); resc=false; \
;     { const float dl=rm; mhat=fadd_s(mhat,dl); \
;       _Pragma("unroll") for(int r=0;r<16;++r){P0[r]=fsub_s(P0[r],dl);P1[r]=fsub_s(P1[r],dl);} \
;       _Pragma("unroll") for(int r=0;r<16;++r)negm[r]=-mhat; asm volatile("":"+v"(negm)); } \
;     _Pragma("unroll") for(int r=0;r<16;++r)P0[r]=__builtin_amdgcn_exp2f(P0[r]); }while(0)
;   #define ROT() do{sl_prev=sl_cur;sl_cur=sl_next;sl_next=(sl_next==(NSLOT-1)*SLOTB)?0:sl_next+SLOTB;}while(0)
; template<int MODE,int THRL> __device__ __forceinline__ void attn_unit(const bf16*Qw0,int PQ,const bf16*__restrict__ Kh,int PK,const bf16*__restrict__ Vh,int PV,bf16*Ow0,int PO,int NT,int nabase,int nar0,const float*rpbh,char*shm,int&rot,bool pre,bool hasn,long dKn,long dVn){
;     ...
;   if(pre){WAIT_BAR(0);}else if(MODE==2){WAIT_BAR(4);}else{WAIT_BAR(3);}
;   qkt(pA0,pA1,Kbase+sl_cur,qr,negm,r32,hi);asm volatile("s_nop 15\n\ts_nop 7":"+v"(pA0),"+v"(pA1));CMASK(pA0,pA1,0);
;   START(pA0,pA1);
;   _Pragma("unroll") for(int r=0;r<16;++r)pA1[r]=__builtin_amdgcn_exp2f(pA1[r]);
;   WAIT_BAR(0);
;   DMA_K(3,sl_cur);DMA_V(1,sl_next);
;   ROT();
;   kload8(kf,kp0+sl_cur);
;   if(MODE==2){WAIT_BAR(3);}else{WAIT_BAR(2);}
.LBB0_486:
	v_lshlrev_b32_e32 v0, 10, v214
	v_lshlrev_b32_e32 v35, 4, v213
	v_add3_u32 v44, s82, v0, v35
	ds_read_b128 v[36:39], v44
	ds_read_b128 v[40:43], v44 offset:512
	v_or_b32_e32 v221, v0, v35
	s_add_i32 s10, s15, s82
	s_waitcnt vmcnt(3) lgkmcnt(1)
	v_mfma_f32_32x32x16_bf16 v[18:33], v[36:39], v[148:151], v[2:17]
	v_lshl_add_u64 v[196:197], v[206:207], 0, s[54:55]
	s_and_b32 s3, s3, 0x3fffffc0
	s_lshl_b32 s3, s3, 2
	s_add_i32 s3, s3, 0x12000
	s_mov_b32 s86, 1
	v_lshlrev_b32_e32 v224, 4, v214
	v_lshl_add_u32 v218, v213, 2, s3
	s_waitcnt lgkmcnt(0)
	v_mfma_f32_32x32x16_bf16 v[2:17], v[40:43], v[148:151], v[2:17]
	ds_read_b128 v[36:39], v44 offset:2048
	ds_read_b128 v[40:43], v44 offset:2560
	s_waitcnt vmcnt(2) lgkmcnt(1)
	v_mfma_f32_32x32x16_bf16 v[18:33], v[36:39], v[140:143], v[18:33]
	s_waitcnt lgkmcnt(0)
	v_mfma_f32_32x32x16_bf16 v[2:17], v[40:43], v[140:143], v[2:17]
	ds_read_b128 v[36:39], v44 offset:4096
	ds_read_b128 v[40:43], v44 offset:4608
	s_waitcnt vmcnt(1) lgkmcnt(1)
	v_mfma_f32_32x32x16_bf16 v[18:33], v[36:39], v[132:135], v[18:33]
	s_waitcnt lgkmcnt(0)
	v_mfma_f32_32x32x16_bf16 v[2:17], v[40:43], v[132:135], v[2:17]
	ds_read_b128 v[36:39], v44 offset:6144
	ds_read_b128 v[40:43], v44 offset:6656
	s_waitcnt vmcnt(0) lgkmcnt(1)
	v_mfma_f32_32x32x16_bf16 v[18:33], v[36:39], v[128:131], v[18:33]
	v_lshlrev_b32_e32 v36, 1, v34
	v_lshlrev_b32_e32 v34, 4, v34
	v_and_b32_e32 v34, 0xc0, v34
	v_lshl_or_b32 v217, v214, 8, v34
	v_and_b32_e32 v216, 32, v36
	v_or3_b32 v220, v216, v215, v217
	s_waitcnt lgkmcnt(0)
	v_mfma_f32_32x32x16_bf16 v[2:17], v[40:43], v[128:131], v[2:17]
	s_nop 15
	s_nop 7
	s_nop 0
	v_max3_f32 v0, v18, v19, v2
	v_max3_f32 v34, v20, v21, v3
	s_nop 0
	v_max3_f32 v0, v0, v4, v5
	v_max3_f32 v34, v34, v24, v25
	s_nop 0
	v_max3_f32 v0, v0, v22, v23
	v_max3_f32 v34, v34, v8, v9
	s_nop 0
	v_max3_f32 v0, v0, v6, v7
	v_max3_f32 v34, v34, v28, v29
	s_nop 0
	v_max3_f32 v0, v0, v26, v27
	v_max3_f32 v34, v34, v12, v13
	s_nop 0
	v_max3_f32 v0, v0, v10, v11
	v_max3_f32 v34, v34, v32, v33
	s_nop 0
	v_max3_f32 v0, v0, v30, v31
	v_max3_f32 v34, v34, v16, v17
	s_nop 0
	v_max3_f32 v0, v0, v14, v15
	s_nop 0
	v_max_f32_e32 v0, v0, v34
	s_nop 0
	v_mov_b32_e32 v34, v0
	s_nop 1
	v_permlane32_swap_b32_e32 v0, v34
	v_max_f32_e32 v0, v0, v34
	s_nop 0
	v_max_f32_e32 v0, s100, v0
	v_add_f32_e32 v219, v1, v0
	v_sub_f32_e32 v2, v2, v0
	v_sub_f32_e32 v3, v3, v0
	v_sub_f32_e32 v18, v18, v0
	v_sub_f32_e32 v19, v19, v0
	v_sub_f32_e32 v20, v20, v0
	s_nop 0
	v_xor_b32_e32 v48, 0x80000000, v219
	v_mov_b32_e32 v49, v48
	v_mov_b32_e32 v50, v48
	v_mov_b32_e32 v51, v48
	v_mov_b32_e32 v52, v48
	v_mov_b32_e32 v53, v48
	v_mov_b32_e32 v54, v48
	v_mov_b32_e32 v55, v48
	v_mov_b32_e32 v56, v48
	v_mov_b32_e32 v57, v48
	v_mov_b32_e32 v58, v48
	v_mov_b32_e32 v59, v48
	v_mov_b32_e32 v60, v48
	v_mov_b32_e32 v61, v48
	v_mov_b32_e32 v62, v48
	v_mov_b32_e32 v63, v48
	s_waitcnt vmcnt(0) lgkmcnt(0)
	s_barrier
	v_sub_f32_e32 v4, v4, v0
	v_sub_f32_e32 v21, v21, v0
	v_sub_f32_e32 v5, v5, v0
	v_sub_f32_e32 v22, v22, v0
	v_sub_f32_e32 v6, v6, v0
	v_sub_f32_e32 v23, v23, v0
	v_sub_f32_e32 v7, v7, v0
	v_sub_f32_e32 v24, v24, v0
	v_sub_f32_e32 v8, v8, v0
	v_sub_f32_e32 v25, v25, v0
	v_sub_f32_e32 v9, v9, v0
	v_sub_f32_e32 v26, v26, v0
	v_sub_f32_e32 v10, v10, v0
	v_sub_f32_e32 v27, v27, v0
	v_sub_f32_e32 v11, v11, v0
	v_sub_f32_e32 v28, v28, v0
	v_sub_f32_e32 v12, v12, v0
	v_sub_f32_e32 v29, v29, v0
	v_sub_f32_e32 v13, v13, v0
	v_sub_f32_e32 v30, v30, v0
	v_sub_f32_e32 v14, v14, v0
	v_sub_f32_e32 v31, v31, v0
	v_sub_f32_e32 v15, v15, v0
	v_sub_f32_e32 v32, v32, v0
	v_sub_f32_e32 v16, v16, v0
	v_sub_f32_e32 v33, v33, v0
	v_sub_f32_e32 v0, v17, v0
	v_exp_f32_e32 v64, v2
	v_exp_f32_e32 v65, v3
	v_lshl_add_u64 v[2:3], v[204:205], 0, s[58:59]
	s_mov_b32 s11, m0
	s_mov_b32 m0, s10
	s_nop 0
	global_load_lds_dwordx4 v[2:3], off
	s_mov_b32 m0, s11
	s_lshl_b32 s10, s43, 1
	v_exp_f32_e32 v79, v0
	s_add_i32 s10, s10, s33
	s_mov_b32 s11, m0
	s_mov_b32 m0, s10
	s_nop 0
	global_load_lds_dwordx4 v[196:197], off
	s_mov_b32 m0, s11
	v_add_u32_e32 v0, s43, v221
	ds_read_b128 v[188:191], v0
	ds_read_b128 v[184:187], v0 offset:512
	ds_read_b128 v[180:183], v0 offset:2048
	ds_read_b128 v[176:179], v0 offset:2560
	ds_read_b128 v[172:175], v0 offset:4096
	ds_read_b128 v[168:171], v0 offset:4608
	ds_read_b128 v[164:167], v0 offset:6144
	ds_read_b128 v[160:163], v0 offset:6656
	v_exp_f32_e32 v80, v18
	v_exp_f32_e32 v81, v19
	v_exp_f32_e32 v82, v20
	v_exp_f32_e32 v83, v21
	v_exp_f32_e32 v84, v22
	v_exp_f32_e32 v85, v23
	v_exp_f32_e32 v86, v24
	v_exp_f32_e32 v87, v25
	v_exp_f32_e32 v88, v26
	v_exp_f32_e32 v89, v27
	v_exp_f32_e32 v90, v28
	v_exp_f32_e32 v91, v29
	v_exp_f32_e32 v92, v30
	v_exp_f32_e32 v93, v31
	v_exp_f32_e32 v94, v32
	v_exp_f32_e32 v95, v33
	v_exp_f32_e32 v66, v4
	v_exp_f32_e32 v67, v5
	v_exp_f32_e32 v68, v6
	v_exp_f32_e32 v69, v7
	v_exp_f32_e32 v70, v8
	v_exp_f32_e32 v71, v9
	v_exp_f32_e32 v72, v10
	v_exp_f32_e32 v73, v11
	v_exp_f32_e32 v74, v12
	v_exp_f32_e32 v75, v13
	v_exp_f32_e32 v76, v14
	v_exp_f32_e32 v77, v15
	v_exp_f32_e32 v78, v16
	s_waitcnt vmcnt(2) lgkmcnt(0)
	s_barrier
	s_cmpk_lg_i32 s43, 0x4000
	s_cselect_b32 s52, s52, 0
	s_andn2_b64 vcc, exec, s[8:9]
	v_cmp_gt_u32_e64 s[8:9], 32, v211
	s_cbranch_vccnz .LBB0_502
	v_mov_b32_e32 v14, v1
	v_mov_b32_e32 v15, v1
	s_mov_b64 s[10:11], 0x168000
	v_mov_b32_e32 v0, v1
	v_mov_b32_e32 v2, v1
	v_mov_b32_e32 v3, v1
	v_mov_b32_e32 v4, v1
	v_mov_b32_e32 v5, v1
	v_mov_b32_e32 v6, v1
	v_mov_b32_e32 v7, v1
	v_mov_b32_e32 v8, v1
	v_mov_b32_e32 v9, v1
	v_mov_b32_e32 v10, v1
	v_mov_b32_e32 v11, v1
	v_mov_b32_e32 v12, v1
	v_mov_b32_e32 v13, v1
	v_mov_b64_e32 v[46:47], v[14:15]
	v_mov_b64_e32 v[30:31], v[14:15]
	v_lshl_add_u64 v[198:199], v[206:207], 0, s[58:59]
	v_lshl_add_u64 v[200:201], v[204:205], 0, s[10:11]
	v_mov_b32_e32 v225, 0
	s_mov_b32 s67, 6
	v_mov_b64_e32 v[44:45], v[12:13]
	v_mov_b64_e32 v[42:43], v[10:11]
	v_mov_b64_e32 v[40:41], v[8:9]
	v_mov_b64_e32 v[38:39], v[6:7]
	v_mov_b64_e32 v[36:37], v[4:5]
	v_mov_b64_e32 v[34:35], v[2:3]
	v_mov_b64_e32 v[32:33], v[0:1]
	v_mov_b64_e32 v[28:29], v[12:13]
	v_mov_b64_e32 v[26:27], v[10:11]
	v_mov_b64_e32 v[24:25], v[8:9]
	v_mov_b64_e32 v[22:23], v[6:7]
	v_mov_b64_e32 v[20:21], v[4:5]
	v_mov_b64_e32 v[18:19], v[2:3]
	v_mov_b64_e32 v[16:17], v[0:1]
